# OUTA epilogue: non-temporal loads for the f32 residual x
# speedup vs baseline: 1.0008x; 1.0008x over previous
; __device__ __forceinline__ void st16_wt(void* p, u32x4 v) { if (WT_STORES) asm volatile("global_store_dwordx4 %0, %1, off sc1\n\ts_nop 1" :: "v"(p), "v"(v) : "memory"); else *(u32x4*)p = v; }
; __device__ __forceinline__ unsigned cvt_pk_f16(float lo, float hi) { const f32x2_t v = {lo, hi}; const f16x2_t h = __builtin_convertvector(v, f16x2_t); return __builtin_bit_cast(unsigned, h); }
;     __device__ __forceinline__ void operator()(const f32x4 (&acc)[2][2][4][2], const Unit& u, int wr, int wc, int fr, int fq, bool, PG8_LAS float*, PG8_LAS const float*) const {
;         f32x4 pre[FIRST ? 4 : 1][2][2]; u32x4 preh[FIRST ? 1 : 4][2]; float ssq[8];
;         const size_t off0 = (size_t)(u.pm * BM + wr * 64 + fr) * 1024 + u.pn * BM + wc * 32 + 4 * fq;
;         const size_t offw = off0 + ((fq & 1) ? 12 : 0);
;     ...
;         EPO_LOAD(0); EPO_LOAD(1); EPO_LOAD(2); EPO_LOAD(3);
; #pragma unroll
;         for (int rg = 0; rg < 8; ++rg) {
;             const int ai = rg >> 2, m = rg & 3;
;             float ss = 0.f;
; #pragma unroll
;             for (int bj = 0; bj < 2; ++bj) {
;                 f32x4 p0, p1;
;                 if (FIRST) { p0 = pre[rg & 3][bj][0]; p1 = pre[rg & 3][bj][1]; }
;                 else { const u32x4 L = preh[rg & 3][bj]; const unsigned lx = L.x, ly = L.y, lz = L.z, lw = L.w; u32x2 X, Y; unsigned a0, b0, a1, b1; swap2(lx, lz, a0, b0); swap2(ly, lw, a1, b1);
;                        X.x = a0; X.y = a1; Y.x = b0; Y.y = b1; p0 = f16x4_to_f32(X); p1 = f16x4_to_f32(Y); }
;                 const f32x4 o0 = p0 + acc[ai][bj][m][0], o1 = p1 + acc[ai][bj][m][1];
;                 if (FIRST) {
;                     const unsigned x0 = cvt_pk_f16(o0[0], o0[1]), x1 = cvt_pk_f16(o0[2], o0[3]), y0 = cvt_pk_f16(o1[0], o1[1]), y1 = cvt_pk_f16(o1[2], o1[3]);
;                     unsigned a0, b0, a1, b1; swap2(x0, y0, a0, b0); swap2(x1, y1, a1, b1);
;                     u32x4 w; w.x = a0; w.y = a1; w.z = b0; w.w = b1;
;                     st16_wt(xh + offw + EPO_ROW(rg) + bj * HALF, w);
;                     ss += ((o0[0] * o0[0] + o0[1] * o0[1]) + (o0[2] * o0[2] + o0[3] * o0[3])) + ((o1[0] * o1[0] + o1[1] * o1[1]) + (o1[2] * o1[2] + o1[3] * o1[3]));
.LBB0_437:
	s_lshl_b32 s13, s20, 8
	s_add_i32 s13, s13, s40
	v_or_b32_e32 v128, s13, v181
	v_ashrrev_i32_e32 v129, 31, v128
	s_lshl_b32 s20, s51, 8
	v_lshlrev_b64 v[128:129], 10, v[128:129]
	s_ashr_i32 s21, s20, 31
	v_lshl_add_u64 v[192:193], v[128:129], 0, s[20:21]
	v_or_b32_e32 v192, v192, v180
	v_lshl_add_u64 v[194:195], v[192:193], 2, s[44:45]
	global_load_dwordx4 v[202:205], v[194:195], off nt
	global_load_dwordx4 v[206:209], v[194:195], off offset:64 nt
	global_load_dwordx4 v[210:213], v[194:195], off offset:512 nt
	global_load_dwordx4 v[214:217], v[194:195], off offset:576 nt
	v_add_co_u32_e32 v128, vcc, s39, v194
	s_mov_b32 s2, 0x20000
	s_nop 0
	v_addc_co_u32_e32 v129, vcc, 0, v195, vcc
	global_load_dwordx4 v[172:175], v[128:129], off nt
	global_load_dwordx4 v[168:171], v[128:129], off offset:64 nt
	global_load_dwordx4 v[164:167], v[128:129], off offset:512 nt
	global_load_dwordx4 v[160:163], v[128:129], off offset:576 nt
	v_add_co_u32_e32 v128, vcc, s2, v194
	s_mov_b32 s2, 0x30000
	s_nop 0
	v_addc_co_u32_e32 v129, vcc, 0, v195, vcc
	global_load_dwordx4 v[156:159], v[128:129], off nt
	global_load_dwordx4 v[152:155], v[128:129], off offset:64 nt
	global_load_dwordx4 v[148:151], v[128:129], off offset:512 nt
	global_load_dwordx4 v[144:147], v[128:129], off offset:576 nt
	v_add_co_u32_e32 v128, vcc, s2, v194
	v_lshl_add_u64 v[192:193], v[192:193], 1, v[182:183]
	s_nop 0
	v_addc_co_u32_e32 v129, vcc, 0, v195, vcc
	global_load_dwordx4 v[140:143], v[128:129], off nt
	global_load_dwordx4 v[136:139], v[128:129], off offset:64 nt
	global_load_dwordx4 v[132:135], v[128:129], off offset:512 nt
	s_nop 0
	global_load_dwordx4 v[128:131], v[128:129], off offset:576 nt
	s_mov_b32 s2, 0x80000
	s_waitcnt vmcnt(0)
	v_pk_add_f32 v[196:197], v[114:115], v[204:205]
	v_pk_add_f32 v[202:203], v[112:113], v[202:203]
	v_pk_add_f32 v[118:119], v[118:119], v[208:209]
	v_pk_add_f32 v[116:117], v[116:117], v[206:207]
	v_cvt_pk_f16_f32 v112, v202, v203
	v_cvt_pk_f16_f32 v113, v196, v197
	v_cvt_pk_f16_f32 v114, v116, v117
	v_cvt_pk_f16_f32 v115, v118, v119
	s_nop 0
	v_permlane16_swap_b32_e32 v112, v114
	v_permlane16_swap_b32_e32 v113, v115
	v_pk_add_f32 v[122:123], v[122:123], v[212:213]
	v_pk_add_f32 v[120:121], v[120:121], v[210:211]
	v_pk_add_f32 v[126:127], v[126:127], v[216:217]
	v_pk_add_f32 v[124:125], v[124:125], v[214:215]
	global_store_dwordx4 v[192:193], v[112:115], off
	v_pk_add_f32 v[110:111], v[110:111], v[174:175]
	v_pk_add_f32 v[108:109], v[108:109], v[172:173]
	v_cvt_pk_f16_f32 v112, v120, v121
	v_cvt_pk_f16_f32 v113, v122, v123
	v_cvt_pk_f16_f32 v114, v124, v125
	v_cvt_pk_f16_f32 v115, v126, v127
	s_nop 0
	v_permlane16_swap_b32_e32 v112, v114
	v_permlane16_swap_b32_e32 v113, v115
	global_store_dwordx4 v[192:193], v[112:115], off offset:256
	v_pk_add_f32 v[170:171], v[106:107], v[170:171]
	v_pk_add_f32 v[168:169], v[104:105], v[168:169]
	v_mov_b32_e32 v113, v120
	v_mov_b32_e32 v120, v203
	v_mov_b32_e32 v112, v202
	v_pk_mul_f32 v[114:115], v[120:121], v[120:121]
	v_cvt_pk_f16_f32 v104, v108, v109
	v_pk_fma_f32 v[112:113], v[112:113], v[112:113], v[114:115]
	v_mov_b32_e32 v115, v122
	v_mov_b32_e32 v122, v197
	v_mov_b32_e32 v114, v196
	v_pk_mul_f32 v[120:121], v[122:123], v[122:123]
	v_cvt_pk_f16_f32 v105, v110, v111
	v_pk_fma_f32 v[114:115], v[114:115], v[114:115], v[120:121]
	v_cvt_pk_f16_f32 v106, v168, v169
	v_pk_add_f32 v[112:113], v[112:113], v[114:115]
	v_mov_b32_e32 v115, v124
	v_mov_b32_e32 v124, v117
	v_mov_b32_e32 v114, v116
	v_pk_mul_f32 v[116:117], v[124:125], v[124:125]
	v_cvt_pk_f16_f32 v107, v170, v171
	v_pk_fma_f32 v[114:115], v[114:115], v[114:115], v[116:117]
	v_mov_b32_e32 v117, v126
	v_mov_b32_e32 v126, v119
	v_mov_b32_e32 v116, v118
	v_pk_mul_f32 v[118:119], v[126:127], v[126:127]
	v_permlane16_swap_b32_e32 v104, v106
	v_pk_fma_f32 v[116:117], v[116:117], v[116:117], v[118:119]
	v_permlane16_swap_b32_e32 v105, v107
	v_pk_add_f32 v[114:115], v[114:115], v[116:117]
	v_pk_add_f32 v[102:103], v[102:103], v[166:167]
	v_pk_add_f32 v[112:113], v[112:113], v[114:115]
	v_pk_add_f32 v[100:101], v[100:101], v[164:165]
	v_pk_add_f32 v[196:197], v[112:113], v[112:113] op_sel:[0,1] op_sel_hi:[1,0]
	v_add_co_u32_e32 v112, vcc, s2, v194
	s_mov_b32 s2, 0x8000
	s_nop 0
	v_addc_co_u32_e32 v113, vcc, 0, v195, vcc
	v_add_co_u32_e32 v172, vcc, s2, v192
	global_load_dwordx4 v[124:127], v[112:113], off nt
	global_load_dwordx4 v[120:123], v[112:113], off offset:64 nt
	global_load_dwordx4 v[116:119], v[112:113], off offset:512 nt
	s_nop 0
	global_load_dwordx4 v[112:115], v[112:113], off offset:576 nt
	v_addc_co_u32_e32 v173, vcc, 0, v193, vcc
	global_store_dwordx4 v[172:173], v[104:107], off
	s_mov_b32 s2, 0x90000
	v_pk_add_f32 v[94:95], v[94:95], v[158:159]
	v_mul_f32_e32 v104, v109, v109
	v_mul_f32_e32 v105, v111, v111
	v_fmac_f32_e32 v104, v108, v108
	v_fmac_f32_e32 v105, v110, v110
	v_add_f32_e32 v104, v104, v105
	v_mul_f32_e32 v105, v169, v169
	v_mul_f32_e32 v106, v171, v171
	v_fmac_f32_e32 v105, v168, v168
	v_fmac_f32_e32 v106, v170, v170
	v_add_f32_e32 v105, v105, v106
	v_add_f32_e32 v108, v104, v105
	v_pk_add_f32 v[104:105], v[98:99], v[162:163]
	v_pk_add_f32 v[106:107], v[96:97], v[160:161]
	v_cvt_pk_f16_f32 v96, v100, v101
	v_cvt_pk_f16_f32 v97, v102, v103
	v_cvt_pk_f16_f32 v98, v106, v107
	v_cvt_pk_f16_f32 v99, v104, v105
	s_nop 0
	v_permlane16_swap_b32_e32 v96, v98
	v_permlane16_swap_b32_e32 v97, v99
	global_store_dwordx4 v[172:173], v[96:99], off offset:256
	v_pk_add_f32 v[92:93], v[92:93], v[156:157]
	v_pk_add_f32 v[154:155], v[90:91], v[154:155]
	v_mul_f32_e32 v96, v101, v101
	v_mul_f32_e32 v97, v103, v103
	v_fmac_f32_e32 v96, v100, v100
; __device__ __forceinline__ void st16_wt(void* p, u32x4 v) { if (WT_STORES) asm volatile("global_store_dwordx4 %0, %1, off sc1\n\ts_nop 1" :: "v"(p), "v"(v) : "memory"); else *(u32x4*)p = v; }
; __device__ __forceinline__ unsigned cvt_pk_f16(float lo, float hi) { const f32x2_t v = {lo, hi}; const f16x2_t h = __builtin_convertvector(v, f16x2_t); return __builtin_bit_cast(unsigned, h); }
;     static __device__ __forceinline__ void swap2(unsigned a, unsigned b, unsigned& ra, unsigned& rb) { auto r = __builtin_amdgcn_permlane16_swap(a, b, false, false); const unsigned r0 = r[0], r1 = r[1]; ra = r0; rb = r1; }
; #define EPO_LOAD(rg) do { _Pragma("unroll") for (int bj = 0; bj < 2; ++bj) { \
;             if (FIRST) { _Pragma("unroll") for (int n = 0; n < 2; ++n) pre[(rg) & 3][bj][n] = *(const f32x4*)(base + off0 + EPO_ROW(rg) + bj * HALF + n * 16); } \
;             else preh[(rg) & 3][bj] = *(const u32x4*)(xh + offw + EPO_ROW(rg) + bj * HALF); } } while (0)
;     __device__ __forceinline__ void operator()(const f32x4 (&acc)[2][2][4][2], const Unit& u, int wr, int wc, int fr, int fq, bool, PG8_LAS float*, PG8_LAS const float*) const {
;     ...
;                 const f32x4 o0 = p0 + acc[ai][bj][m][0], o1 = p1 + acc[ai][bj][m][1];
;                 if (FIRST) {
;                     const unsigned x0 = cvt_pk_f16(o0[0], o0[1]), x1 = cvt_pk_f16(o0[2], o0[3]), y0 = cvt_pk_f16(o1[0], o1[1]), y1 = cvt_pk_f16(o1[2], o1[3]);
;                     unsigned a0, b0, a1, b1; swap2(x0, y0, a0, b0); swap2(x1, y1, a1, b1);
;                     u32x4 w; w.x = a0; w.y = a1; w.z = b0; w.w = b1;
;                     st16_wt(xh + offw + EPO_ROW(rg) + bj * HALF, w);
;                     ss += ((o0[0] * o0[0] + o0[1] * o0[1]) + (o0[2] * o0[2] + o0[3] * o0[3])) + ((o1[0] * o1[0] + o1[1] * o1[1]) + (o1[2] * o1[2] + o1[3] * o1[3]));
;                 } else {
;                     st16_wt(out + off0 + EPO_ROW(rg) + bj * HALF, __builtin_bit_cast(u32x4, o0));
;                     st16_wt(out + off0 + EPO_ROW(rg) + bj * HALF + 16, __builtin_bit_cast(u32x4, o1));
;                 }
;             }
;             if (rg + 4 < 8) EPO_LOAD(rg + 4);
	v_fmac_f32_e32 v97, v102, v102
	v_add_f32_e32 v96, v96, v97
	v_mul_f32_e32 v97, v107, v107
	v_mul_f32_e32 v98, v105, v105
	v_fmac_f32_e32 v97, v106, v106
	v_fmac_f32_e32 v98, v104, v104
	v_add_f32_e32 v97, v97, v98
	v_add_f32_e32 v96, v96, v97
	v_add_f32_e32 v160, v108, v96
	v_add_co_u32_e32 v96, vcc, s2, v194
	v_pk_add_f32 v[152:153], v[88:89], v[152:153]
	s_nop 0
	v_addc_co_u32_e32 v97, vcc, 0, v195, vcc
	v_cvt_pk_f16_f32 v88, v92, v93
	v_cvt_pk_f16_f32 v89, v94, v95
	v_cvt_pk_f16_f32 v90, v152, v153
	v_cvt_pk_f16_f32 v91, v154, v155
	v_add_co_u32_e32 v156, vcc, s39, v192
	v_permlane16_swap_b32_e32 v88, v90
	v_permlane16_swap_b32_e32 v89, v91
	v_addc_co_u32_e32 v157, vcc, 0, v193, vcc
	global_load_dwordx4 v[108:111], v[96:97], off nt
	global_load_dwordx4 v[104:107], v[96:97], off offset:64 nt
	global_load_dwordx4 v[100:103], v[96:97], off offset:512 nt
	s_nop 0
	global_load_dwordx4 v[96:99], v[96:97], off offset:576 nt
	v_pk_add_f32 v[86:87], v[86:87], v[150:151]
	global_store_dwordx4 v[156:157], v[88:91], off
	v_pk_add_f32 v[84:85], v[84:85], v[148:149]
	s_mov_b32 s2, 0xa0000
	v_mul_f32_e32 v88, v93, v93
	v_mul_f32_e32 v89, v95, v95
	v_fmac_f32_e32 v88, v92, v92
	v_fmac_f32_e32 v89, v94, v94
	v_add_f32_e32 v88, v88, v89
	v_mul_f32_e32 v89, v153, v153
	v_mul_f32_e32 v90, v155, v155
	v_fmac_f32_e32 v89, v152, v152
	v_fmac_f32_e32 v90, v154, v154
	v_add_f32_e32 v89, v89, v90
	v_add_f32_e32 v92, v88, v89
	v_pk_add_f32 v[88:89], v[82:83], v[146:147]
	v_pk_add_f32 v[90:91], v[80:81], v[144:145]
	v_cvt_pk_f16_f32 v80, v84, v85
	v_cvt_pk_f16_f32 v81, v86, v87
	v_cvt_pk_f16_f32 v82, v90, v91
	v_cvt_pk_f16_f32 v83, v88, v89
	s_nop 0
	v_permlane16_swap_b32_e32 v80, v82
	v_permlane16_swap_b32_e32 v81, v83
	global_store_dwordx4 v[156:157], v[80:83], off offset:256
	v_pk_add_f32 v[78:79], v[78:79], v[142:143]
	v_pk_add_f32 v[76:77], v[76:77], v[140:141]
	v_mul_f32_e32 v80, v85, v85
	v_mul_f32_e32 v81, v87, v87
	v_fmac_f32_e32 v80, v84, v84
	v_fmac_f32_e32 v81, v86, v86
	v_add_f32_e32 v80, v80, v81
	v_mul_f32_e32 v81, v91, v91
	v_mul_f32_e32 v82, v89, v89
	v_fmac_f32_e32 v81, v90, v90
	v_fmac_f32_e32 v82, v88, v88
	v_add_f32_e32 v81, v81, v82
	v_add_f32_e32 v80, v80, v81
	v_add_f32_e32 v144, v92, v80
	v_add_co_u32_e32 v80, vcc, s2, v194
	v_pk_add_f32 v[138:139], v[74:75], v[138:139]
	s_nop 0
	v_addc_co_u32_e32 v81, vcc, 0, v195, vcc
	v_pk_add_f32 v[136:137], v[72:73], v[136:137]
	s_mov_b32 s2, 0x18000
	v_cvt_pk_f16_f32 v72, v76, v77
	v_cvt_pk_f16_f32 v73, v78, v79
	v_cvt_pk_f16_f32 v74, v136, v137
	v_cvt_pk_f16_f32 v75, v138, v139
	v_add_co_u32_e32 v140, vcc, s2, v192
	v_permlane16_swap_b32_e32 v72, v74
	v_permlane16_swap_b32_e32 v73, v75
	v_addc_co_u32_e32 v141, vcc, 0, v193, vcc
	global_load_dwordx4 v[92:95], v[80:81], off nt
	global_load_dwordx4 v[88:91], v[80:81], off offset:64 nt
	global_load_dwordx4 v[84:87], v[80:81], off offset:512 nt
	s_nop 0
	global_load_dwordx4 v[80:83], v[80:81], off offset:576 nt
	v_pk_add_f32 v[70:71], v[70:71], v[134:135]
	global_store_dwordx4 v[140:141], v[72:75], off
	v_pk_add_f32 v[68:69], v[68:69], v[132:133]
	s_mov_b32 s2, 0xb0000
	v_mul_f32_e32 v72, v77, v77
	v_mul_f32_e32 v73, v79, v79
	v_fmac_f32_e32 v72, v76, v76
	v_fmac_f32_e32 v73, v78, v78
	v_add_f32_e32 v72, v72, v73
	v_mul_f32_e32 v73, v137, v137
	v_mul_f32_e32 v74, v139, v139
	v_fmac_f32_e32 v73, v136, v136
	v_fmac_f32_e32 v74, v138, v138
	v_add_f32_e32 v73, v73, v74
	v_add_f32_e32 v76, v72, v73
	v_pk_add_f32 v[72:73], v[66:67], v[130:131]
	v_pk_add_f32 v[74:75], v[64:65], v[128:129]
	v_cvt_pk_f16_f32 v64, v68, v69
	v_cvt_pk_f16_f32 v65, v70, v71
	v_cvt_pk_f16_f32 v66, v74, v75
	v_cvt_pk_f16_f32 v67, v72, v73
	s_nop 0
	v_permlane16_swap_b32_e32 v64, v66
	v_permlane16_swap_b32_e32 v65, v67
	global_store_dwordx4 v[140:141], v[64:67], off offset:256
	s_waitcnt vmcnt(17)
	v_pk_add_f32 v[62:63], v[62:63], v[126:127]
	v_pk_add_f32 v[60:61], v[60:61], v[124:125]
	v_mul_f32_e32 v64, v69, v69
	v_mul_f32_e32 v65, v71, v71
	v_fmac_f32_e32 v64, v68, v68
	v_fmac_f32_e32 v65, v70, v70
	v_add_f32_e32 v64, v64, v65
	v_mul_f32_e32 v65, v75, v75
	v_mul_f32_e32 v66, v73, v73
	v_fmac_f32_e32 v65, v74, v74
	v_fmac_f32_e32 v66, v72, v72
	v_add_f32_e32 v65, v65, v66
	v_add_f32_e32 v64, v64, v65
	v_add_f32_e32 v128, v76, v64
	v_add_co_u32_e32 v64, vcc, s2, v194
	s_waitcnt vmcnt(16)
	v_pk_add_f32 v[122:123], v[54:55], v[122:123]
	v_addc_co_u32_e32 v65, vcc, 0, v195, vcc
	global_load_dwordx4 v[76:79], v[64:65], off nt
	global_load_dwordx4 v[72:75], v[64:65], off offset:64 nt
	global_load_dwordx4 v[68:71], v[64:65], off offset:512 nt
	s_nop 0
	global_load_dwordx4 v[64:67], v[64:65], off offset:576 nt
	v_pk_add_f32 v[120:121], v[52:53], v[120:121]
	s_mov_b32 s2, 0x40000
	v_cvt_pk_f16_f32 v52, v60, v61
	v_cvt_pk_f16_f32 v53, v62, v63
	v_cvt_pk_f16_f32 v54, v120, v121
	v_cvt_pk_f16_f32 v55, v122, v123
	v_add_co_u32_e32 v124, vcc, s2, v192
	v_permlane16_swap_b32_e32 v52, v54
	v_permlane16_swap_b32_e32 v53, v55
	v_addc_co_u32_e32 v125, vcc, 0, v193, vcc
	global_store_dwordx4 v[124:125], v[52:55], off
	s_waitcnt vmcnt(16)
	v_pk_add_f32 v[46:47], v[46:47], v[110:111]
	v_pk_add_f32 v[44:45], v[44:45], v[108:109]
	v_pk_add_f32 v[52:53], v[58:59], v[118:119]
	v_pk_add_f32 v[54:55], v[56:57], v[116:117]
	v_pk_add_f32 v[56:57], v[50:51], v[114:115]
	v_pk_add_f32 v[58:59], v[48:49], v[112:113]
	v_cvt_pk_f16_f32 v48, v54, v55
	v_cvt_pk_f16_f32 v49, v52, v53
	v_cvt_pk_f16_f32 v50, v58, v59
	v_cvt_pk_f16_f32 v51, v56, v57
	s_nop 0
	v_permlane16_swap_b32_e32 v48, v50
	v_permlane16_swap_b32_e32 v49, v51
	global_store_dwordx4 v[124:125], v[48:51], off offset:256
	s_mov_b32 s2, 0x48000
	s_waitcnt vmcnt(11)
; __device__ __forceinline__ float sum_x16(float v) { float a, b; swap16(v, a, b); return a + b; }
; __device__ __forceinline__ float sum_x32(float v) { float a, b; swap32(v, a, b); return a + b; }
; __device__ __forceinline__ void st16_wt(void* p, u32x4 v) { if (WT_STORES) asm volatile("global_store_dwordx4 %0, %1, off sc1\n\ts_nop 1" :: "v"(p), "v"(v) : "memory"); else *(u32x4*)p = v; }
; #define EPO_LOAD(rg) do { _Pragma("unroll") for (int bj = 0; bj < 2; ++bj) { \
;             if (FIRST) { _Pragma("unroll") for (int n = 0; n < 2; ++n) pre[(rg) & 3][bj][n] = *(const f32x4*)(base + off0 + EPO_ROW(rg) + bj * HALF + n * 16); } \
;             else preh[(rg) & 3][bj] = *(const u32x4*)(xh + offw + EPO_ROW(rg) + bj * HALF); } } while (0)
;     __device__ __forceinline__ void operator()(const f32x4 (&acc)[2][2][4][2], const Unit& u, int wr, int wc, int fr, int fq, bool, PG8_LAS float*, PG8_LAS const float*) const {
;     ...
;                     ss += ((o0[0] * o0[0] + o0[1] * o0[1]) + (o0[2] * o0[2] + o0[3] * o0[3])) + ((o1[0] * o1[0] + o1[1] * o1[1]) + (o1[2] * o1[2] + o1[3] * o1[3]));
;                 } else {
;                     st16_wt(out + off0 + EPO_ROW(rg) + bj * HALF, __builtin_bit_cast(u32x4, o0));
;                     st16_wt(out + off0 + EPO_ROW(rg) + bj * HALF + 16, __builtin_bit_cast(u32x4, o1));
;                 }
;             }
;             if (rg + 4 < 8) EPO_LOAD(rg + 4);
;             if (FIRST) { ss = sum_x16(ss); ss = sum_x32(ss); ssq[rg] = ss; }
;         }
;         if (FIRST) {
; #pragma unroll
;             for (int hh = 0; hh < 2; ++hh) {
;                 const float v = (fq == 0) ? ssq[4 * hh] : (fq == 1) ? ssq[4 * hh + 1] : (fq == 2) ? ssq[4 * hh + 2] : ssq[4 * hh + 3];
;                 const int r = u.pm * BM + hh * HALF + wr * 64 + fq * 16 + fr;
;                 part[(size_t)r * 16 + u.pn * 4 + wc] = v;
;             }
	v_pk_add_f32 v[30:31], v[30:31], v[94:95]
	v_mul_f32_e32 v48, v61, v61
	v_mul_f32_e32 v49, v63, v63
	v_fmac_f32_e32 v48, v60, v60
	v_fmac_f32_e32 v49, v62, v62
	v_add_f32_e32 v48, v48, v49
	v_mul_f32_e32 v49, v121, v121
	v_mul_f32_e32 v50, v123, v123
	v_fmac_f32_e32 v49, v120, v120
	v_fmac_f32_e32 v50, v122, v122
	v_add_f32_e32 v49, v49, v50
	v_add_f32_e32 v48, v48, v49
	v_mul_f32_e32 v49, v55, v55
	v_mul_f32_e32 v50, v53, v53
	v_fmac_f32_e32 v49, v54, v54
	v_fmac_f32_e32 v50, v52, v52
	v_add_f32_e32 v49, v49, v50
	v_mul_f32_e32 v50, v59, v59
	v_mul_f32_e32 v51, v57, v57
	v_fmac_f32_e32 v50, v58, v58
	v_fmac_f32_e32 v51, v56, v56
	v_add_f32_e32 v50, v50, v51
	v_add_f32_e32 v49, v49, v50
	v_pk_add_f32 v[50:51], v[38:39], v[106:107]
	v_pk_add_f32 v[52:53], v[36:37], v[104:105]
	v_cvt_pk_f16_f32 v36, v44, v45
	v_cvt_pk_f16_f32 v37, v46, v47
	v_cvt_pk_f16_f32 v38, v52, v53
	v_cvt_pk_f16_f32 v39, v50, v51
	v_add_co_u32_e32 v54, vcc, s2, v192
	v_permlane16_swap_b32_e32 v36, v38
	v_permlane16_swap_b32_e32 v37, v39
	v_addc_co_u32_e32 v55, vcc, 0, v193, vcc
	global_store_dwordx4 v[54:55], v[36:39], off
	v_pk_add_f32 v[28:29], v[28:29], v[92:93]
	s_mov_b32 s2, 0x50000
	v_pk_add_f32 v[36:37], v[42:43], v[102:103]
	v_pk_add_f32 v[38:39], v[40:41], v[100:101]
	v_pk_add_f32 v[40:41], v[34:35], v[98:99]
	v_pk_add_f32 v[42:43], v[32:33], v[96:97]
	v_cvt_pk_f16_f32 v32, v38, v39
	v_cvt_pk_f16_f32 v33, v36, v37
	v_cvt_pk_f16_f32 v34, v42, v43
	v_cvt_pk_f16_f32 v35, v40, v41
	s_nop 0
	v_permlane16_swap_b32_e32 v32, v34
	v_permlane16_swap_b32_e32 v33, v35
	global_store_dwordx4 v[54:55], v[32:35], off offset:256
	s_waitcnt vmcnt(7)
	v_pk_add_f32 v[10:11], v[10:11], v[78:79]
	v_pk_add_f32 v[8:9], v[8:9], v[76:77]
	v_mul_f32_e32 v32, v45, v45
	v_mul_f32_e32 v33, v47, v47
	v_fmac_f32_e32 v32, v44, v44
	v_fmac_f32_e32 v33, v46, v46
	v_add_f32_e32 v32, v32, v33
	v_mul_f32_e32 v33, v53, v53
	v_mul_f32_e32 v34, v51, v51
	v_fmac_f32_e32 v33, v52, v52
	v_fmac_f32_e32 v34, v50, v50
	v_add_f32_e32 v33, v33, v34
	v_add_f32_e32 v32, v32, v33
	v_mul_f32_e32 v33, v39, v39
	v_mul_f32_e32 v34, v37, v37
	v_fmac_f32_e32 v33, v38, v38
	v_fmac_f32_e32 v34, v36, v36
	v_add_f32_e32 v33, v33, v34
	v_mul_f32_e32 v34, v43, v43
	v_mul_f32_e32 v35, v41, v41
	v_fmac_f32_e32 v34, v42, v42
	v_fmac_f32_e32 v35, v40, v40
	v_add_f32_e32 v34, v34, v35
	v_add_f32_e32 v33, v33, v34
	v_pk_add_f32 v[34:35], v[22:23], v[90:91]
	v_pk_add_f32 v[36:37], v[20:21], v[88:89]
	v_cvt_pk_f16_f32 v20, v28, v29
	v_cvt_pk_f16_f32 v21, v30, v31
	v_cvt_pk_f16_f32 v22, v36, v37
	v_cvt_pk_f16_f32 v23, v34, v35
	v_add_co_u32_e32 v38, vcc, s2, v192
	v_permlane16_swap_b32_e32 v20, v22
	v_permlane16_swap_b32_e32 v21, v23
	v_addc_co_u32_e32 v39, vcc, 0, v193, vcc
	global_store_dwordx4 v[38:39], v[20:23], off
	s_mov_b32 s2, 0x58000
	s_waitcnt vmcnt(6)
	v_pk_add_f32 v[6:7], v[6:7], v[70:71]
	v_pk_add_f32 v[20:21], v[26:27], v[86:87]
	v_pk_add_f32 v[22:23], v[24:25], v[84:85]
	v_pk_add_f32 v[24:25], v[18:19], v[82:83]
	v_pk_add_f32 v[26:27], v[16:17], v[80:81]
	v_cvt_pk_f16_f32 v16, v22, v23
	v_cvt_pk_f16_f32 v17, v20, v21
	v_cvt_pk_f16_f32 v18, v26, v27
	v_cvt_pk_f16_f32 v19, v24, v25
	s_nop 0
	v_permlane16_swap_b32_e32 v16, v18
	v_permlane16_swap_b32_e32 v17, v19
	global_store_dwordx4 v[38:39], v[16:19], off offset:256
	v_pk_add_f32 v[4:5], v[4:5], v[68:69]
	s_waitcnt vmcnt(6)
	v_pk_add_f32 v[14:15], v[14:15], v[66:67]
	v_mul_f32_e32 v16, v29, v29
	v_mul_f32_e32 v17, v31, v31
	v_fmac_f32_e32 v16, v28, v28
	v_fmac_f32_e32 v17, v30, v30
	v_add_f32_e32 v16, v16, v17
	v_mul_f32_e32 v17, v37, v37
	v_mul_f32_e32 v18, v35, v35
	v_fmac_f32_e32 v17, v36, v36
	v_fmac_f32_e32 v18, v34, v34
	v_add_f32_e32 v17, v17, v18
	v_add_f32_e32 v16, v16, v17
	v_mul_f32_e32 v17, v23, v23
	v_mul_f32_e32 v18, v21, v21
	v_fmac_f32_e32 v17, v22, v22
	v_fmac_f32_e32 v18, v20, v20
	v_add_f32_e32 v17, v17, v18
	v_mul_f32_e32 v18, v27, v27
	v_mul_f32_e32 v19, v25, v25
	v_fmac_f32_e32 v18, v26, v26
	v_fmac_f32_e32 v19, v24, v24
	v_add_f32_e32 v18, v18, v19
	v_add_f32_e32 v17, v17, v18
	v_pk_add_f32 v[18:19], v[2:3], v[74:75]
	v_pk_add_f32 v[20:21], v[0:1], v[72:73]
	v_cvt_pk_f16_f32 v0, v8, v9
	v_cvt_pk_f16_f32 v1, v10, v11
	v_cvt_pk_f16_f32 v2, v20, v21
	v_cvt_pk_f16_f32 v3, v18, v19
	v_add_co_u32_e32 v22, vcc, s2, v192
	v_permlane16_swap_b32_e32 v0, v2
	v_permlane16_swap_b32_e32 v1, v3
	v_addc_co_u32_e32 v23, vcc, 0, v193, vcc
	v_pk_add_f32 v[12:13], v[12:13], v[64:65]
	global_store_dwordx4 v[22:23], v[0:3], off
	v_add_f32_e32 v48, v48, v49
	v_add_f32_e32 v32, v32, v33
	v_cvt_pk_f16_f32 v0, v4, v5
	v_cvt_pk_f16_f32 v1, v6, v7
	v_cvt_pk_f16_f32 v2, v12, v13
	v_cvt_pk_f16_f32 v3, v14, v15
	s_nop 0
	v_permlane16_swap_b32_e32 v0, v2
	v_permlane16_swap_b32_e32 v1, v3
	global_store_dwordx4 v[22:23], v[0:3], off offset:256
	v_add_f32_e32 v16, v16, v17
	v_mov_b32_e32 v197, v196
	v_mul_f32_e32 v0, v9, v9
	v_mul_f32_e32 v1, v11, v11
	v_fmac_f32_e32 v0, v8, v8
	v_fmac_f32_e32 v1, v10, v10
	v_add_f32_e32 v0, v0, v1
	v_mul_f32_e32 v1, v21, v21
	v_mul_f32_e32 v2, v19, v19
	v_fmac_f32_e32 v1, v20, v20
	v_fmac_f32_e32 v2, v18, v18
	v_add_f32_e32 v1, v1, v2
	v_add_f32_e32 v0, v0, v1
	v_mul_f32_e32 v1, v5, v5
	v_mul_f32_e32 v2, v7, v7
	v_fmac_f32_e32 v1, v4, v4
	v_fmac_f32_e32 v2, v6, v6
	v_add_f32_e32 v1, v1, v2
	v_mul_f32_e32 v2, v13, v13
	v_mul_f32_e32 v3, v15, v15
	v_fmac_f32_e32 v2, v12, v12
	v_fmac_f32_e32 v3, v14, v14
	v_add_f32_e32 v2, v2, v3
	v_add_f32_e32 v1, v1, v2
	v_add_f32_e32 v0, v0, v1
	v_mov_b32_e32 v161, v160
	v_mov_b32_e32 v145, v144
	v_mov_b32_e32 v129, v128
	v_mov_b32_e32 v49, v48
	v_mov_b32_e32 v33, v32
	v_mov_b32_e32 v17, v16
	v_mov_b32_e32 v1, v0
	v_permlane16_swap_b32_e32 v196, v197
	v_permlane16_swap_b32_e32 v160, v161
	v_permlane16_swap_b32_e32 v144, v145
	v_permlane16_swap_b32_e32 v128, v129
	v_permlane16_swap_b32_e32 v48, v49
	v_permlane16_swap_b32_e32 v32, v33
	v_permlane16_swap_b32_e32 v16, v17
	v_permlane16_swap_b32_e32 v0, v1
	v_add_f32_e32 v196, v196, v197
	v_add_f32_e32 v160, v160, v161
	v_add_f32_e32 v144, v144, v145
	v_add_f32_e32 v128, v128, v129
	v_add_f32_e32 v48, v48, v49
	v_add_f32_e32 v32, v32, v33
	v_add_f32_e32 v16, v16, v17
	v_add_f32_e32 v2, v0, v1
	v_mov_b32_e32 v197, v196
	v_mov_b32_e32 v161, v160
	v_mov_b32_e32 v145, v144
	v_mov_b32_e32 v129, v128
	v_mov_b32_e32 v49, v48
	v_mov_b32_e32 v33, v32
	v_mov_b32_e32 v17, v16
	v_mov_b32_e32 v3, v2
	v_permlane32_swap_b32_e32 v196, v197
	v_permlane32_swap_b32_e32 v160, v161
	v_permlane32_swap_b32_e32 v144, v145
	v_permlane32_swap_b32_e32 v128, v129
	v_permlane32_swap_b32_e32 v48, v49
	v_permlane32_swap_b32_e32 v32, v33
	v_permlane32_swap_b32_e32 v16, v17
	v_permlane32_swap_b32_e32 v2, v3
	v_cmp_lt_i32_e32 vcc, 1, v198
	s_and_saveexec_b64 s[20:21], vcc
	s_xor_b64 s[20:21], exec, s[20:21]
	s_cbranch_execz .LBB0_443
	v_cmp_lt_i32_e32 vcc, 2, v198
	s_and_saveexec_b64 s[22:23], vcc
	s_xor_b64 s[22:23], exec, s[22:23]
	v_add_f32_e32 v4, v128, v129
	s_andn2_saveexec_b64 s[22:23], s[22:23]
	v_add_f32_e32 v4, v144, v145
	s_or_b64 exec, exec, s[22:23]
